# FFN gate/up weight transposes moved from the bandwidth-bound scan phase (kind 4) into the issue-bound chunk-precompute phase (kind 11), hand-written saddr-form loop run by every wave after its items;
# baseline (speedup 1.0000x reference)
; #define LAS __attribute__((address_space(3)))
; #define INF(i) uniform_ptr((const float*)tab[i])
; __device__ __forceinline__ void tr_matrix(const float* W, int Ksrc, int N, bf16* dst, int ldt, int dcol0, int rowmode, int drow_off, LAS float* scr, int gw, int ngw, int lane, const float* nscale = nullptr, const float* kscale = nullptr) {
;     const int nkb = (Ksrc + 63) / 64, nnb = N / 32, items = nkb * nnb;
;     for (int it = gw; it < items; it += ngw) { const int kb = it / nnb, nb = it - kb * nnb, n0 = nb * 32;
;         const int drow0 = rowmode ? ((n0 >> 7) * 256 + (n0 & 127) + drow_off) : (drow_off + n0);
;         tr_item(W, Ksrc, N, kb * 64, n0, dst, ldt, drow0, dcol0, scr, lane, nscale, kscale); }
; __global__ void __launch_bounds__(NTHREADS, 2) trunk_fwd(Args a) {
;     ...
;                 for (int q = 0; q < 2; ++q) { const int LL = L + q; bf16* fgu = (bf16*)(ws + WS_FGU + (size_t)(LL & 1) * SZ_FFN); bf16* fd = (bf16*)(ws + WS_FD + (size_t)(LL & 1) * SZ_FFN);
;                     tr_matrix(INF(27) + (size_t)LL * D * DFF, D, DFF, fgu, D, 0, 1, 0, scr, cw, ncw, lane, nullptr, INF(26) + (size_t)LL * D);
;                     tr_matrix(INF(28) + (size_t)LL * D * DFF, D, DFF, fgu, D, 0, 1, 128, scr, cw, ncw, lane, nullptr, INF(26) + (size_t)LL * D);
.LBB0_314:
	s_cmp_eq_u32 s77, 11
	s_cbranch_scc0 .Ltrp_skip
	v_lshrrev_b32_e32 v1, 3, v185
	v_and_b32_e32 v2, 7, v185
	v_mul_u32_u24_e32 v3, 0x5800, v1
	v_lshl_add_u32 v20, v2, 4, v3
	v_add_u32_e32 v21, 0x2c000, v20
	v_add_u32_e32 v22, 0x58000, v20
	v_add_u32_e32 v23, 0x84000, v20
	v_add_u32_e32 v24, 0xb0000, v20
	v_add_u32_e32 v25, 0xdc000, v20
	v_add_u32_e32 v26, 0x108000, v20
	v_add_u32_e32 v27, 0x134000, v20
	v_lshlrev_b32_e32 v28, 2, v1
	s_mul_i32 s0, s52, 0x3f40
	v_mul_u32_u24_e32 v3, 0x84, v1
	v_lshl_add_u32 v3, v2, 4, v3
	v_add_u32_e32 v29, s0, v3
	v_mul_u32_u24_e32 v3, 0x420, v2
	v_lshl_add_u32 v3, v1, 2, v3
	v_add_u32_e32 v30, s0, v3
	v_lshlrev_b32_e32 v3, 12, v1
	v_lshl_add_u32 v31, v2, 4, v3
	v_add_u32_e32 v32, 0x8000, v31
	v_add_u32_e32 v33, 0x10000, v31
	v_add_u32_e32 v34, 0x18000, v31
	s_mov_b32 s56, 0
.Ltrp_q:
	s_add_i32 s4, s59, s56
	s_mov_b32 s5, 0
.Ltrp_mat:
	v_mov_b32_e32 v3, s92
	s_lshl_b32 s0, s5, 3
	v_add_u32_e32 v4, s0, v3
	ds_read_b64 v[6:7], v3 offset:208
	ds_read_b64 v[8:9], v4 offset:216
	s_waitcnt lgkmcnt(0)
	v_readfirstlane_b32 s8, v6
	v_readfirstlane_b32 s9, v7
	v_readfirstlane_b32 s6, v8
	v_readfirstlane_b32 s7, v9
	s_lshl_b32 s0, s4, 13
	s_add_u32 s8, s8, s0
	s_addc_u32 s9, s9, 0
	s_mul_i32 s0, s4, 0x2c00000
	s_mul_hi_u32 s1, s4, 0x2c00000
	s_add_u32 s6, s6, s0
	s_addc_u32 s7, s7, s1
	s_and_b32 s0, s4, 1
	s_mul_i32 s0, s0, 0x4200000
	s_lshl_b32 s1, s5, 19
	s_add_u32 s0, s0, s1
	s_add_u32 s0, s0, 0x7200000
	s_add_u32 s14, s88, s0
	s_addc_u32 s15, s89, 0
	s_mov_b32 s17, s10
	s_cmpk_lt_i32 s17, 0x1600
	s_cbranch_scc0 .Ltrp_mat_next
; __device__ __forceinline__ unsigned pk_bf16(float lo, float hi) { f32x2e v = {lo, hi}; bf16x2e b = __builtin_convertvector(v, bf16x2e); return __builtin_bit_cast(unsigned, b); }
; #define LAS __attribute__((address_space(3)))
; __device__ __forceinline__ void tr_item(const float* W, int Ksrc, int N, int k0, int n0, bf16* dst, int ldt, int drow0, int dcol0, LAS float* scr, int lane, const float* nscale = nullptr, const float* kscale = nullptr) {
;     f32x4 tv[8]; const int kr_ = lane >> 3, nq_ = lane & 7;
; #pragma unroll
;     for (int i = 0; i < 8; ++i) { const int kk = 8 * i + kr_; const int kr = (k0 + kk < Ksrc) ? (k0 + kk) : (Ksrc - 1); tv[i] = __builtin_nontemporal_load((const f32x4*)(W + (size_t)kr * N + n0 + 4 * nq_)); }
; #pragma unroll
;     for (int i = 0; i < 8; ++i) { const int kk = 8 * i + kr_; const bool ok = (k0 + kk < Ksrc); LAS float* d_ = scr + kk * 33 + 4 * nq_;
;         const float ks_ = (ok && kscale) ? kscale[k0 + kk] : 1.0f;
;         d_[0] = ok ? tv[i].x * ks_ : 0.f; d_[1] = ok ? tv[i].y * ks_ : 0.f; d_[2] = ok ? tv[i].z * ks_ : 0.f; d_[3] = ok ? tv[i].w * ks_ : 0.f; }
;     asm volatile("s_waitcnt lgkmcnt(0)" ::: "memory");
;     const int c = lane & 7;
; #pragma unroll
;     for (int j = 0; j < 4; ++j) { const int n = (lane >> 3) + 8 * j; const LAS float* s = scr + (8 * c) * 33 + n;
;         const float sc = nscale ? nscale[n0 + n] : 1.0f;
;         u32x4 o; o.x = pk_bf16(s[0 * 33] * sc, s[1 * 33] * sc); o.y = pk_bf16(s[2 * 33] * sc, s[3 * 33] * sc); o.z = pk_bf16(s[4 * 33] * sc, s[5 * 33] * sc); o.w = pk_bf16(s[6 * 33] * sc, s[7 * 33] * sc);
;         *(u32x4*)(dst + (size_t)(drow0 + n) * ldt + dcol0 + k0 + 8 * c) = o; }
;     asm volatile("s_waitcnt lgkmcnt(0)" ::: "memory");
; }
; __device__ __forceinline__ void tr_matrix(const float* W, int Ksrc, int N, bf16* dst, int ldt, int dcol0, int rowmode, int drow_off, LAS float* scr, int gw, int ngw, int lane, const float* nscale = nullptr, const float* kscale = nullptr) {
;     ...
;     for (int it = gw; it < items; it += ngw) { const int kb = it / nnb, nb = it - kb * nnb, n0 = nb * 32;
;         const int drow0 = rowmode ? ((n0 >> 7) * 256 + (n0 & 127) + drow_off) : (drow_off + n0);
;         tr_item(W, Ksrc, N, kb * 64, n0, dst, ldt, drow0, dcol0, scr, lane, nscale, kscale); }
.Ltrp_item:
	s_mul_hi_i32 s0, s17, 0x2e8ba2e9
	s_lshr_b32 s1, s0, 31
	s_ashr_i32 s11, s0, 5
	s_add_i32 s11, s11, s1
	s_mul_i32 s0, s11, 0xffffea00
	s_lshl_b32 s28, s17, 5
	s_add_i32 s28, s28, s0
	s_lshl_b32 s57, s11, 6
	s_mul_i32 s0, s11, 0x160000
	s_lshl_b32 s1, s28, 2
	s_add_u32 s0, s0, s1
	s_add_u32 s30, s6, s0
	s_addc_u32 s31, s7, 0
	s_lshl_b32 s0, s57, 2
	s_add_u32 s34, s8, s0
	s_addc_u32 s35, s9, 0
	global_load_dwordx4 v[36:39], v20, s[30:31] nt
	global_load_dwordx4 v[40:43], v21, s[30:31] nt
	global_load_dwordx4 v[44:47], v22, s[30:31] nt
	global_load_dwordx4 v[48:51], v23, s[30:31] nt
	global_load_dwordx4 v[52:55], v24, s[30:31] nt
	global_load_dwordx4 v[56:59], v25, s[30:31] nt
	global_load_dwordx4 v[60:63], v26, s[30:31] nt
	global_load_dwordx4 v[64:67], v27, s[30:31] nt
	global_load_dword v68, v28, s[34:35]
	global_load_dword v69, v28, s[34:35] offset:32
	global_load_dword v70, v28, s[34:35] offset:64
	global_load_dword v71, v28, s[34:35] offset:96
	global_load_dword v72, v28, s[34:35] offset:128
	global_load_dword v73, v28, s[34:35] offset:160
	global_load_dword v74, v28, s[34:35] offset:192
	global_load_dword v75, v28, s[34:35] offset:224
	s_lshr_b32 s0, s28, 7
	s_lshl_b32 s0, s0, 8
	s_and_b32 s1, s28, 0x7f
	s_or_b32 s0, s0, s1
	s_lshl_b32 s0, s0, 12
	s_lshl_b32 s1, s57, 1
	s_add_u32 s0, s0, s1
	s_add_u32 s36, s14, s0
	s_addc_u32 s37, s15, 0
	s_waitcnt vmcnt(0)
	v_mul_f32_e32 v36, v36, v68
	v_mul_f32_e32 v37, v37, v68
	v_mul_f32_e32 v38, v38, v68
	v_mul_f32_e32 v39, v39, v68
	ds_write_b32 v29, v36
	ds_write_b32 v29, v37 offset:4
	ds_write_b32 v29, v38 offset:8
	ds_write_b32 v29, v39 offset:12
	v_mul_f32_e32 v40, v40, v69
	v_mul_f32_e32 v41, v41, v69
	v_mul_f32_e32 v42, v42, v69
	v_mul_f32_e32 v43, v43, v69
	ds_write_b32 v29, v40 offset:1056
	ds_write_b32 v29, v41 offset:1060
	ds_write_b32 v29, v42 offset:1064
	ds_write_b32 v29, v43 offset:1068
	v_mul_f32_e32 v44, v44, v70
	v_mul_f32_e32 v45, v45, v70
	v_mul_f32_e32 v46, v46, v70
	v_mul_f32_e32 v47, v47, v70
	ds_write_b32 v29, v44 offset:2112
	ds_write_b32 v29, v45 offset:2116
	ds_write_b32 v29, v46 offset:2120
	ds_write_b32 v29, v47 offset:2124
	v_mul_f32_e32 v48, v48, v71
	v_mul_f32_e32 v49, v49, v71
	v_mul_f32_e32 v50, v50, v71
	v_mul_f32_e32 v51, v51, v71
	ds_write_b32 v29, v48 offset:3168
	ds_write_b32 v29, v49 offset:3172
	ds_write_b32 v29, v50 offset:3176
	ds_write_b32 v29, v51 offset:3180
	v_mul_f32_e32 v52, v52, v72
	v_mul_f32_e32 v53, v53, v72
	v_mul_f32_e32 v54, v54, v72
	v_mul_f32_e32 v55, v55, v72
	ds_write_b32 v29, v52 offset:4224
	ds_write_b32 v29, v53 offset:4228
	ds_write_b32 v29, v54 offset:4232
	ds_write_b32 v29, v55 offset:4236
	v_mul_f32_e32 v56, v56, v73
	v_mul_f32_e32 v57, v57, v73
	v_mul_f32_e32 v58, v58, v73
	v_mul_f32_e32 v59, v59, v73
	ds_write_b32 v29, v56 offset:5280
	ds_write_b32 v29, v57 offset:5284
	ds_write_b32 v29, v58 offset:5288
	ds_write_b32 v29, v59 offset:5292
	v_mul_f32_e32 v60, v60, v74
	v_mul_f32_e32 v61, v61, v74
	v_mul_f32_e32 v62, v62, v74
	v_mul_f32_e32 v63, v63, v74
	ds_write_b32 v29, v60 offset:6336
	ds_write_b32 v29, v61 offset:6340
	ds_write_b32 v29, v62 offset:6344
	ds_write_b32 v29, v63 offset:6348
	v_mul_f32_e32 v64, v64, v75
	v_mul_f32_e32 v65, v65, v75
	v_mul_f32_e32 v66, v66, v75
	v_mul_f32_e32 v67, v67, v75
	ds_write_b32 v29, v64 offset:7392
	ds_write_b32 v29, v65 offset:7396
	ds_write_b32 v29, v66 offset:7400
	ds_write_b32 v29, v67 offset:7404
	s_waitcnt lgkmcnt(0)
	ds_read_b32 v36, v30
	ds_read_b32 v37, v30 offset:132
	ds_read_b32 v38, v30 offset:264
	ds_read_b32 v39, v30 offset:396
	ds_read_b32 v40, v30 offset:528
	ds_read_b32 v41, v30 offset:660
	ds_read_b32 v42, v30 offset:792
	ds_read_b32 v43, v30 offset:924
	ds_read_b32 v44, v30 offset:32
	ds_read_b32 v45, v30 offset:164
	ds_read_b32 v46, v30 offset:296
	ds_read_b32 v47, v30 offset:428
	ds_read_b32 v48, v30 offset:560
	ds_read_b32 v49, v30 offset:692
	ds_read_b32 v50, v30 offset:824
	ds_read_b32 v51, v30 offset:956
	s_waitcnt lgkmcnt(8)
	v_cvt_pk_bf16_f32 v76, v36, v37
	v_cvt_pk_bf16_f32 v77, v38, v39
	v_cvt_pk_bf16_f32 v78, v40, v41
	v_cvt_pk_bf16_f32 v79, v42, v43
	global_store_dwordx4 v31, v[76:79], s[36:37] nt
	ds_read_b32 v52, v30 offset:64
	ds_read_b32 v53, v30 offset:196
	ds_read_b32 v54, v30 offset:328
	ds_read_b32 v55, v30 offset:460
	ds_read_b32 v56, v30 offset:592
	ds_read_b32 v57, v30 offset:724
	ds_read_b32 v58, v30 offset:856
	ds_read_b32 v59, v30 offset:988
	s_waitcnt lgkmcnt(8)
	v_cvt_pk_bf16_f32 v80, v44, v45
	v_cvt_pk_bf16_f32 v81, v46, v47
	v_cvt_pk_bf16_f32 v82, v48, v49
	v_cvt_pk_bf16_f32 v83, v50, v51
	global_store_dwordx4 v32, v[80:83], s[36:37] nt
	ds_read_b32 v60, v30 offset:96
	ds_read_b32 v61, v30 offset:228
	ds_read_b32 v62, v30 offset:360
	ds_read_b32 v63, v30 offset:492
	ds_read_b32 v64, v30 offset:624
	ds_read_b32 v65, v30 offset:756
	ds_read_b32 v66, v30 offset:888
	ds_read_b32 v67, v30 offset:1020
	s_waitcnt lgkmcnt(8)
	v_cvt_pk_bf16_f32 v84, v52, v53
	v_cvt_pk_bf16_f32 v85, v54, v55
	v_cvt_pk_bf16_f32 v86, v56, v57
	v_cvt_pk_bf16_f32 v87, v58, v59
	global_store_dwordx4 v33, v[84:87], s[36:37] nt
	s_waitcnt lgkmcnt(0)
	v_cvt_pk_bf16_f32 v88, v60, v61
	v_cvt_pk_bf16_f32 v89, v62, v63
	v_cvt_pk_bf16_f32 v90, v64, v65
	v_cvt_pk_bf16_f32 v91, v66, v67
	global_store_dwordx4 v34, v[88:91], s[36:37] nt
	s_add_i32 s17, s17, s16
	s_cmpk_lt_i32 s17, 0x1600
	s_cbranch_scc1 .Ltrp_item
.Ltrp_mat_next:
	s_add_i32 s5, s5, 1
	s_cmp_lt_u32 s5, 2
	s_cbranch_scc1 .Ltrp_mat
	s_add_i32 s56, s56, 1
	s_cmp_lt_u32 s56, 2
	s_cbranch_scc1 .Ltrp_q

; #define INF(i) uniform_ptr((const float*)tab[i])
; __global__ void __launch_bounds__(NTHREADS, 2) trunk_fwd(Args a) {
;     ...
;                 for (int q = 0; q < 2; ++q) { const int LL = L + q; bf16* fgu = (bf16*)(ws + WS_FGU + (size_t)(LL & 1) * SZ_FFN); bf16* fd = (bf16*)(ws + WS_FD + (size_t)(LL & 1) * SZ_FFN);
;                     tr_matrix(INF(27) + (size_t)LL * D * DFF, D, DFF, fgu, D, 0, 1, 0, scr, cw, ncw, lane, nullptr, INF(26) + (size_t)LL * D);
.LBB0_327:
	s_add_i32 s34, s0, s59
	s_bitcmp1_b32 s34, 0
	s_cselect_b32 s28, 0x4200000, 0
	s_add_u32 s42, s75, s28
	s_addc_u32 s43, s79, 0
	s_add_i32 s6, s92, 0
	v_mov_b32_e32 v2, s6
	ds_read_b64 v[0:1], v2 offset:216
	s_mov_b32 s35, s29
	s_lshl_b64 s[62:63], s[34:35], 11
	s_mul_hi_u32 s57, s34, 0xb00000
	s_mul_i32 s56, s34, 0xb00000
	s_waitcnt lgkmcnt(0)
	v_readfirstlane_b32 s7, v1
	v_readfirstlane_b32 s8, v0
	ds_read_b64 v[0:1], v2 offset:208
	s_andn2_b64 vcc, exec, s[36:37]
	v_lshlrev_b32_e32 v96, 2, v34
	v_lshlrev_b32_e32 v40, 1, v36
	s_waitcnt lgkmcnt(0)
	v_readfirstlane_b32 s0, v0
	v_cndmask_b32_e64 v0, 0, 1, s[36:37]
	v_readfirstlane_b32 s1, v1
	v_cmp_ne_u32_e64 s[38:39], 1, v0
	s_branch .LBB0_348
	s_lshl_b64 s[14:15], s[62:63], 2
	s_add_u32 s64, s0, s14
	s_addc_u32 s65, s1, s15
	s_lshl_b64 s[14:15], s[56:57], 2
	s_add_u32 s8, s8, s14
	s_addc_u32 s9, s7, s15
	s_cmp_lg_u64 s[0:1], 0
	v_mov_b32_e32 v41, v97
	v_lshl_add_u64 v[42:43], s[8:9], 0, v[96:97]
	s_cselect_b64 s[66:67], -1, 0
	v_lshl_add_u64 v[44:45], s[42:43], 0, v[40:41]
	s_mov_b32 s7, s5
	s_mov_b32 s8, s4
	s_mov_b32 s9, s2
	s_branch .LBB0_330

; #define INF(i) uniform_ptr((const float*)tab[i])
; __global__ void __launch_bounds__(NTHREADS, 2) trunk_fwd(Args a) {
;     ...
;                     tr_matrix(INF(28) + (size_t)LL * D * DFF, D, DFF, fgu, D, 0, 1, 128, scr, cw, ncw, lane, nullptr, INF(26) + (size_t)LL * D);
;                     tr_matrix(INF(29) + (size_t)LL * DFF * D, DFF, D, fd, DFF, 0, 0, 0, scr, cw, ncw, lane); }
.LBB0_348:
	v_mov_b32_e32 v2, s6
	ds_read_b64 v[0:1], v2 offset:224
	s_and_b64 vcc, exec, s[38:39]
	s_waitcnt lgkmcnt(0)
	v_readfirstlane_b32 s7, v1
	v_readfirstlane_b32 s8, v0
	ds_read_b64 v[0:1], v2 offset:208
	s_waitcnt lgkmcnt(0)
	v_readfirstlane_b32 s1, v1
	v_readfirstlane_b32 s0, v0
	s_branch .LBB0_369
	s_lshl_b64 s[14:15], s[62:63], 2
	s_add_u32 s62, s0, s14
	s_addc_u32 s63, s1, s15
	s_lshl_b64 s[14:15], s[56:57], 2
	s_add_u32 s8, s8, s14
	s_addc_u32 s9, s7, s15
	s_cmp_lg_u64 s[0:1], 0
	v_mov_b32_e32 v41, v97
	v_lshl_add_u64 v[42:43], s[8:9], 0, v[96:97]
	s_cselect_b64 s[56:57], -1, 0
	v_lshl_add_u64 v[40:41], s[42:43], 0, v[40:41]
	s_mov_b32 s7, s5
	s_mov_b32 s8, s4
	s_mov_b32 s9, s2
	s_branch .LBB0_351
